# attention work queue made per-XCD (counter per XCC id): each XCD takes one batch and 4 heads head-major so its 32 CUs stream the same K/V through one L2; pool items row-aligned with the XCD that reads
# speedup vs baseline: 1.0143x; 1.0143x over previous
; template<int THRL,class Extra> __device__ __forceinline__ void attn_phase(char*lds,const AttnTensors&T,const unsigned*stats,unsigned*queue,volatile __attribute__((address_space(3))) unsigned*qw,const Extra&X){
;     ...
;   { int t_=threadIdx.x; asm volatile("":"+v"(t_));
;     if(t_<256)sl[t_]=__hip_atomic_load(stats+t_,__ATOMIC_RELAXED,__HIP_MEMORY_SCOPE_AGENT); }
;   if(threadIdx.x==0)nxt=__hip_atomic_fetch_add(queue,1u,__ATOMIC_RELAXED,__HIP_MEMORY_SCOPE_AGENT);
;   for(;;){
;     if(threadIdx.x==0)qw[0]=nxt;
;     asm volatile("s_waitcnt vmcnt(0) lgkmcnt(0)\n\ts_barrier":::"memory");
;     idx=__builtin_amdgcn_readfirstlane((int)qw[0]);
;     asm volatile("s_waitcnt lgkmcnt(0)\n\ts_barrier":::"memory");
;     if(idx>=N_UNITS)break;
;     if(threadIdx.x==0)nxt=__hip_atomic_fetch_add(queue,1u,__ATOMIC_RELAXED,__HIP_MEMORY_SCOPE_AGENT);
;     AttnUnit u; unit_of(idx,sl,u);
.LBB0_262:
	s_or_b64 exec, exec, s[10:11]
	s_ashr_i32 s5, s4, 31
	s_lshl_b64 s[0:1], s[4:5], 2
	s_add_u32 s0, s8, s0
	s_addc_u32 s1, s9, s1
	s_add_u32 s54, s0, 0x4c303800
	s_addc_u32 s55, s1, 0
	s_getreg_b32 s100, hwreg(HW_REG_XCC_ID, 0, 4)
	s_and_b32 s100, s100, 7
	s_lshl_b32 s100, s100, 2
	s_add_u32 s54, s54, s100
	s_addc_u32 s55, s55, 0
	v_mov_b32_e32 v237, 0
	s_and_saveexec_b64 s[4:5], s[90:91]
	s_cbranch_execz .LBB0_266
	s_mov_b64 s[12:13], exec
	v_mbcnt_lo_u32_b32 v1, s12, 0
	v_mbcnt_hi_u32_b32 v1, s13, v1
	v_cmp_eq_u32_e32 vcc, 0, v1
	s_and_saveexec_b64 s[10:11], vcc
	s_cbranch_execz .LBB0_265
	s_bcnt1_i32_b64 s0, s[12:13]
	v_mov_b32_e32 v2, s0
	global_atomic_add v2, v0, v2, s[54:55] sc0
.LBB0_265:
	s_or_b64 exec, exec, s[10:11]
	s_waitcnt vmcnt(0)
	v_readfirstlane_b32 s0, v2
	s_nop 1
	v_add_u32_e32 v237, s0, v1
	s_getreg_b32 s100, hwreg(HW_REG_XCC_ID, 0, 4)
	v_mov_b32_e32 v3, s100
	v_and_b32_e32 v3, 7, v3
	v_lshrrev_b32_e32 v4, 6, v237
	v_and_b32_e32 v4, 3, v4
	v_lshlrev_b32_e32 v4, 2, v4
	v_and_b32_e32 v5, 1, v3
	v_mul_u32_u24_e32 v5, 0x1122, v5
	v_xor_b32_e32 v5, 0x1267, v5
	v_lshrrev_b32_e32 v5, v4, v5
	v_and_b32_e32 v5, 15, v5
	v_sub_u32_e32 v5, 7, v5
	v_lshrrev_b32_e32 v4, 1, v3
	v_lshl_or_b32 v5, v4, 3, v5
	v_and_b32_e32 v4, 63, v237
	v_lshl_or_b32 v5, v4, 5, v5
	v_lshrrev_b32_e32 v4, 8, v237
	v_cmp_eq_u32_e64 s[100:101], 0, v4
	v_subrev_u32_e32 v4, 0x100, v237
	v_lshl_add_u32 v3, v3, 5, v4
	v_lshrrev_b32_e32 v4, 5, v4
	v_lshl_add_u32 v3, v4, 8, v3
	v_add_u32_e32 v3, 0x800, v3
	v_cndmask_b32_e64 v237, v3, v5, s[100:101]

; template<int THRL,class Extra> __device__ __forceinline__ void attn_phase(char*lds,const AttnTensors&T,const unsigned*stats,unsigned*queue,volatile __attribute__((address_space(3))) unsigned*qw,const Extra&X){
;     ...
;   for(;;){
;     if(threadIdx.x==0)qw[0]=nxt;
;     asm volatile("s_waitcnt vmcnt(0) lgkmcnt(0)\n\ts_barrier":::"memory");
;     idx=__builtin_amdgcn_readfirstlane((int)qw[0]);
;     asm volatile("s_waitcnt lgkmcnt(0)\n\ts_barrier":::"memory");
;     if(idx>=N_UNITS)break;
;     if(threadIdx.x==0)nxt=__hip_atomic_fetch_add(queue,1u,__ATOMIC_RELAXED,__HIP_MEMORY_SCOPE_AGENT);
;     AttnUnit u; unit_of(idx,sl,u);
.LBB0_275:
	s_or_b64 exec, exec, s[6:7]
	s_waitcnt vmcnt(0)
	v_readfirstlane_b32 s0, v2
	s_nop 1
	v_add_u32_e32 v237, s0, v1
	s_getreg_b32 s100, hwreg(HW_REG_XCC_ID, 0, 4)
	v_mov_b32_e32 v3, s100
	v_and_b32_e32 v3, 7, v3
	v_lshrrev_b32_e32 v4, 6, v237
	v_and_b32_e32 v4, 3, v4
	v_lshlrev_b32_e32 v4, 2, v4
	v_and_b32_e32 v5, 1, v3
	v_mul_u32_u24_e32 v5, 0x1122, v5
	v_xor_b32_e32 v5, 0x1267, v5
	v_lshrrev_b32_e32 v5, v4, v5
	v_and_b32_e32 v5, 15, v5
	v_sub_u32_e32 v5, 7, v5
	v_lshrrev_b32_e32 v4, 1, v3
	v_lshl_or_b32 v5, v4, 3, v5
	v_and_b32_e32 v4, 63, v237
	v_lshl_or_b32 v5, v4, 5, v5
	v_lshrrev_b32_e32 v4, 8, v237
	v_cmp_eq_u32_e64 s[100:101], 0, v4
	v_subrev_u32_e32 v4, 0x100, v237
	v_lshl_add_u32 v3, v3, 5, v4
	v_lshrrev_b32_e32 v4, 5, v4
	v_lshl_add_u32 v3, v4, 8, v3
	v_add_u32_e32 v3, 0x800, v3
	v_cndmask_b32_e64 v237, v3, v5, s[100:101]

.LBB0_280:
	s_add_u32 s2, s12, s56
	s_addc_u32 s24, s13, s57
	s_add_u32 s28, s2, 0x80000
	s_addc_u32 s29, s24, 0
	s_add_i32 s19, s22, s84
	s_mov_b32 m0, s19
	s_nop 0
	global_load_lds_dwordx4 v245, s[28:29]
	s_add_i32 s19, s22, s86
	s_mov_b32 m0, s19
	s_nop 0
	global_load_lds_dwordx4 v247, s[28:29]
	s_add_u32 s28, s16, s56
	s_addc_u32 s29, s17, s57
	s_add_u32 s50, s28, 0x40000
	s_addc_u32 s51, s29, 0
	s_lshl_b32 s19, s1, 1
	s_add_i32 s19, s19, s85
	s_mov_b32 m0, s19
	s_nop 0
	global_load_lds_dwordx4 v246, s[50:51]
	s_addk_i32 s19, 0x2000
	s_mov_b32 m0, s19
	s_nop 0
	global_load_lds_dwordx4 v248, s[50:51]
	v_add_f32_e32 v1, v96, v97
	v_add_f32_e32 v1, v98, v1
	v_add_f32_e32 v1, v99, v1
	s_lshl_b32 s18, s18, 1
	v_add_f32_e32 v1, v100, v1
	v_add_u32_e32 v221, s18, v251
	v_add_f32_e32 v1, v101, v1
	v_cvt_pk_bf16_f32 v172, v96, v97
	v_cvt_pk_bf16_f32 v173, v98, v99
	s_waitcnt lgkmcnt(7)
	v_mfma_f32_32x32x16_bf16 v[112:127], v[204:207], v[164:167], 0
	s_nop 0
	v_add_f32_e32 v1, v102, v1
	v_add_f32_e32 v1, v103, v1
	v_add_f32_e32 v1, v104, v1
	v_add_f32_e32 v1, v105, v1
	v_cvt_pk_bf16_f32 v174, v100, v101
	v_cvt_pk_bf16_f32 v175, v102, v103
	s_waitcnt lgkmcnt(6)
	v_mfma_f32_32x32x16_bf16 v[128:143], v[196:199], v[164:167], 0
	v_add_f32_e32 v1, v106, v1
	v_add_f32_e32 v1, v107, v1
	v_add_f32_e32 v1, v108, v1
	v_add_f32_e32 v1, v109, v1
	v_cvt_pk_bf16_f32 v168, v104, v105
	v_cvt_pk_bf16_f32 v169, v106, v107
	s_waitcnt lgkmcnt(5)
	v_mfma_f32_32x32x16_bf16 v[112:127], v[200:203], v[156:159], v[112:127]
	s_nop 0
	v_add_f32_e32 v1, v110, v1
	v_add_f32_e32 v1, v111, v1
	v_add_f32_e32 v1, v80, v1
	v_add_f32_e32 v1, v81, v1
	v_cvt_pk_bf16_f32 v170, v108, v109
	v_cvt_pk_bf16_f32 v171, v110, v111
	s_waitcnt lgkmcnt(4)
	v_mfma_f32_32x32x16_bf16 v[128:143], v[192:195], v[156:159], v[128:143]
	s_nop 0
	v_add_f32_e32 v1, v82, v1
	v_add_f32_e32 v1, v83, v1
	v_add_f32_e32 v1, v84, v1
	v_add_f32_e32 v1, v85, v1
	v_cvt_pk_bf16_f32 v160, v80, v81
	v_cvt_pk_bf16_f32 v161, v82, v83
	s_waitcnt lgkmcnt(3)
	v_mfma_f32_32x32x16_bf16 v[112:127], v[188:191], v[148:151], v[112:127]
	s_nop 0
	v_add_f32_e32 v1, v86, v1
	v_add_f32_e32 v1, v87, v1
	v_add_f32_e32 v1, v88, v1
	v_add_f32_e32 v1, v89, v1
	v_cvt_pk_bf16_f32 v162, v84, v85
	v_cvt_pk_bf16_f32 v163, v86, v87
	s_waitcnt lgkmcnt(2)
	v_mfma_f32_32x32x16_bf16 v[128:143], v[184:187], v[148:151], v[128:143]
	s_nop 0
	v_add_f32_e32 v1, v90, v1
	v_add_f32_e32 v1, v91, v1
	v_add_f32_e32 v1, v92, v1
	v_add_f32_e32 v1, v93, v1
	v_cvt_pk_bf16_f32 v152, v88, v89
	v_cvt_pk_bf16_f32 v153, v90, v91
	s_waitcnt lgkmcnt(1)
	v_mfma_f32_32x32x16_bf16 v[112:127], v[180:183], v[144:147], v[112:127]
	s_nop 0
	v_add_f32_e32 v1, v94, v1
	v_add_f32_e32 v1, v95, v1
	v_add_f32_e32 v1, 0, v1
	v_cvt_pk_bf16_f32 v154, v92, v93
	v_cvt_pk_bf16_f32 v155, v94, v95
	s_waitcnt lgkmcnt(0)
	v_mfma_f32_32x32x16_bf16 v[128:143], v[176:179], v[144:147], v[128:143]
	ds_read_b64_tr_b16 v[10:11], v221 offset:49152
	ds_read_b64_tr_b16 v[12:13], v221 offset:49664
	ds_read_b64_tr_b16 v[6:7], v221 offset:53248
	ds_read_b64_tr_b16 v[8:9], v221 offset:53760
	ds_read_b64_tr_b16 v[2:3], v221 offset:50176
	ds_read_b64_tr_b16 v[4:5], v221 offset:50688
	v_add_f32_e32 v219, v215, v218
	v_add_f32_e32 v84, v215, v219
	v_add_f32_e32 v85, v215, v84
	v_add_f32_e32 v88, v250, v85
	v_add_f32_e32 v89, v215, v88
	v_add_f32_e32 v82, v216, v218
	v_pk_add_f32 v[100:101], v[88:89], v[116:117]
	v_add_f32_e32 v88, v215, v89
	v_add_f32_e32 v83, v215, v82
	v_add_f32_e32 v89, v215, v88
	v_add_f32_e32 v86, v215, v83
	v_add_f32_e32 v92, v250, v89
	v_add_f32_e32 v87, v215, v86
	v_add_f32_e32 v93, v215, v92
	v_pk_add_f32 v[14:15], v[82:83], v[128:129]
	v_pk_add_f32 v[82:83], v[86:87], v[130:131]
	v_add_f32_e32 v86, v250, v87
	v_pk_add_f32 v[104:105], v[92:93], v[120:121]
	v_add_f32_e32 v92, v215, v93
	v_add_f32_e32 v87, v215, v86
	v_add_f32_e32 v93, v215, v92
	v_add_f32_e32 v90, v215, v87
	v_add_f32_e32 v96, v250, v93
	v_add_f32_e32 v91, v215, v90
	v_add_f32_e32 v97, v215, v96
	v_pk_add_f32 v[98:99], v[84:85], v[114:115]
	v_pk_add_f32 v[84:85], v[86:87], v[132:133]
	v_pk_add_f32 v[86:87], v[90:91], v[134:135]
	v_add_f32_e32 v90, v250, v91
	v_pk_add_f32 v[108:109], v[96:97], v[124:125]
	v_add_f32_e32 v96, v215, v97
	v_pk_add_f32 v[80:81], v[218:219], v[112:113]
	v_add_f32_e32 v91, v215, v90
	v_add_f32_e32 v97, v215, v96
	v_add_f32_e32 v94, v215, v91
	v_pk_add_f32 v[110:111], v[96:97], v[126:127]
	v_max_f32_e32 v96, v80, v81
	v_pk_add_f32 v[102:103], v[88:89], v[118:119]
	v_add_f32_e32 v95, v215, v94
	v_max3_f32 v97, v98, v99, v15
	v_max3_f32 v96, v96, v14, v82
	v_pk_add_f32 v[88:89], v[90:91], v[136:137]
	v_pk_add_f32 v[90:91], v[94:95], v[138:139]
	v_add_f32_e32 v94, v250, v95
	v_max3_f32 v96, v96, v83, v100
	v_max3_f32 v97, v97, v102, v103
	v_pk_add_f32 v[106:107], v[92:93], v[122:123]
	v_add_f32_e32 v95, v215, v94
	v_max3_f32 v96, v96, v101, v84
	v_max3_f32 v97, v97, v86, v87
	v_pk_add_f32 v[92:93], v[94:95], v[140:141]
	v_add_f32_e32 v94, v215, v95
	v_max3_f32 v96, v96, v85, v104
	v_max3_f32 v97, v97, v106, v107
	v_add_f32_e32 v95, v215, v94
	v_max3_f32 v96, v96, v105, v88
	v_max3_f32 v97, v97, v90, v91
	v_pk_add_f32 v[94:95], v[94:95], v[142:143]
	v_max3_f32 v96, v96, v89, v108
	v_max3_f32 v97, v97, v110, v111
	v_max3_f32 v96, v96, v109, v92
	v_max3_f32 v97, v97, v94, v95
	v_max3_f32 v96, v96, v93, v97
	v_mov_b32_e32 v97, v96
	s_nop 1
	v_permlane32_swap_b32_e32 v96, v97
	v_max_f32_e32 v97, v97, v97
	v_max_f32_e32 v96, v96, v96
	v_max_f32_e32 v96, v96, v97
	v_cmp_lt_f32_e32 vcc, s20, v96
	s_cmp_lg_u64 vcc, 0
	v_add_f32_e32 v1, v254, v1
	s_cselect_b64 s[58:59], -1, 0
	s_cbranch_vccnz .LBB0_288

.LBB0_283:
	v_subrev_u32_e32 v14, 64, v223
	v_cvt_f32_i32_e32 v14, v14
	s_add_i32 s18, s1, 0x2000
	s_cmpk_lg_i32 s1, 0x4000
	s_cselect_b32 s19, s18, 0
	v_fma_f32 v188, v215, v14, -v252
	s_add_u32 s50, s2, 0xa0000
	s_addc_u32 s51, s24, 0
	s_add_i32 s2, s1, s84
	s_mov_b32 m0, s2
	s_nop 0
	global_load_lds_dwordx4 v245, s[50:51]
	s_add_i32 s2, s1, s86
	s_add_u32 s28, s28, 0x60000
	s_mov_b32 m0, s2
	s_nop 0
	global_load_lds_dwordx4 v247, s[50:51]
	s_addc_u32 s29, s29, 0
	s_lshl_b32 s2, s19, 1
	s_add_i32 s2, s2, s85
	s_mov_b32 m0, s2
	s_nop 0
	global_load_lds_dwordx4 v246, s[28:29]
	s_addk_i32 s2, 0x2000
	s_mov_b32 m0, s2
	s_nop 0
	global_load_lds_dwordx4 v248, s[28:29]
	v_add_f32_e32 v14, v96, v97
	v_add_f32_e32 v14, v98, v14
	v_add_f32_e32 v14, v99, v14
	s_lshl_b32 s2, s22, 1
	v_add_f32_e32 v14, v100, v14
	v_add_u32_e32 v218, s2, v251
	v_add_f32_e32 v14, v101, v14
	v_cvt_pk_bf16_f32 v172, v96, v97
	v_cvt_pk_bf16_f32 v173, v98, v99
	v_mfma_f32_32x32x16_bf16 v[112:127], v[112:115], v[164:167], 0
	s_nop 0
	v_add_f32_e32 v14, v102, v14
	v_add_f32_e32 v14, v103, v14
	v_add_f32_e32 v14, v104, v14
	v_add_f32_e32 v14, v105, v14
	v_cvt_pk_bf16_f32 v174, v100, v101
	v_cvt_pk_bf16_f32 v175, v102, v103
	v_mfma_f32_32x32x16_bf16 v[128:143], v[128:131], v[164:167], 0
	v_add_f32_e32 v14, v106, v14
	v_add_f32_e32 v14, v107, v14
	v_add_f32_e32 v14, v108, v14
	v_add_f32_e32 v14, v109, v14
	v_cvt_pk_bf16_f32 v168, v104, v105
	v_cvt_pk_bf16_f32 v169, v106, v107
	v_mfma_f32_32x32x16_bf16 v[112:127], v[184:187], v[156:159], v[112:127]
	s_nop 0
	v_add_f32_e32 v14, v110, v14
	v_add_f32_e32 v14, v111, v14
	v_add_f32_e32 v14, v80, v14
	v_add_f32_e32 v14, v81, v14
	v_cvt_pk_bf16_f32 v170, v108, v109
	v_cvt_pk_bf16_f32 v171, v110, v111
	v_mfma_f32_32x32x16_bf16 v[128:143], v[180:183], v[156:159], v[128:143]
	s_nop 0
	v_add_f32_e32 v14, v82, v14
	v_add_f32_e32 v14, v83, v14
	v_add_f32_e32 v14, v84, v14
	v_add_f32_e32 v14, v85, v14
	v_cvt_pk_bf16_f32 v160, v80, v81
	v_cvt_pk_bf16_f32 v161, v82, v83
	v_mfma_f32_32x32x16_bf16 v[112:127], v[176:179], v[148:151], v[112:127]
	v_mfma_f32_32x32x16_bf16 v[128:143], v[10:13], v[148:151], v[128:143]
	v_add_f32_e32 v10, v86, v14
	v_add_f32_e32 v10, v87, v10
	v_add_f32_e32 v10, v88, v10
	v_add_f32_e32 v10, v89, v10
	v_cvt_pk_bf16_f32 v162, v84, v85
	v_cvt_pk_bf16_f32 v163, v86, v87
	v_mfma_f32_32x32x16_bf16 v[112:127], v[6:9], v[144:147], v[112:127]
	v_add_f32_e32 v6, v90, v10
	v_add_f32_e32 v6, v91, v6
	v_add_f32_e32 v6, v92, v6
	v_add_f32_e32 v6, v93, v6
	v_cvt_pk_bf16_f32 v152, v88, v89
	v_cvt_pk_bf16_f32 v153, v90, v91
	v_mfma_f32_32x32x16_bf16 v[128:143], v[2:5], v[144:147], v[128:143]
	v_add_f32_e32 v2, v94, v6
	v_add_f32_e32 v2, v95, v2
	v_add_f32_e32 v176, 0, v2
	v_cvt_pk_bf16_f32 v154, v92, v93
	v_cvt_pk_bf16_f32 v155, v94, v95
	ds_read_b64_tr_b16 v[10:11], v218 offset:49152
	ds_read_b64_tr_b16 v[12:13], v218 offset:49664
	ds_read_b64_tr_b16 v[6:7], v218 offset:53248
	ds_read_b64_tr_b16 v[8:9], v218 offset:53760
	ds_read_b64_tr_b16 v[2:3], v218 offset:50176
	ds_read_b64_tr_b16 v[4:5], v218 offset:50688
	v_add_f32_e32 v189, v215, v188
	v_add_f32_e32 v84, v215, v189
	v_add_f32_e32 v85, v215, v84
	v_add_f32_e32 v88, v250, v85
	v_add_f32_e32 v89, v215, v88
	v_add_f32_e32 v82, v216, v188
	v_pk_add_f32 v[100:101], v[88:89], v[116:117]
	v_add_f32_e32 v88, v215, v89
	v_add_f32_e32 v83, v215, v82
	v_add_f32_e32 v89, v215, v88
	v_add_f32_e32 v86, v215, v83
	v_add_f32_e32 v92, v250, v89
	v_add_f32_e32 v87, v215, v86
	v_add_f32_e32 v93, v215, v92
	v_pk_add_f32 v[14:15], v[82:83], v[128:129]
	v_pk_add_f32 v[82:83], v[86:87], v[130:131]
	v_add_f32_e32 v86, v250, v87
	v_pk_add_f32 v[104:105], v[92:93], v[120:121]
	v_add_f32_e32 v92, v215, v93
	v_add_f32_e32 v87, v215, v86
	v_add_f32_e32 v93, v215, v92
	v_add_f32_e32 v90, v215, v87
	v_add_f32_e32 v96, v250, v93
	v_add_f32_e32 v91, v215, v90
	v_add_f32_e32 v97, v215, v96
	v_pk_add_f32 v[98:99], v[84:85], v[114:115]
	v_pk_add_f32 v[84:85], v[86:87], v[132:133]
	v_pk_add_f32 v[86:87], v[90:91], v[134:135]
	v_add_f32_e32 v90, v250, v91
	v_pk_add_f32 v[108:109], v[96:97], v[124:125]
	v_add_f32_e32 v96, v215, v97
	v_pk_add_f32 v[80:81], v[188:189], v[112:113]
	v_add_f32_e32 v91, v215, v90
	v_add_f32_e32 v97, v215, v96
	v_add_f32_e32 v94, v215, v91
	v_pk_add_f32 v[110:111], v[96:97], v[126:127]
	v_max_f32_e32 v96, v80, v81
	v_pk_add_f32 v[102:103], v[88:89], v[118:119]
	v_add_f32_e32 v95, v215, v94
	v_max3_f32 v97, v98, v99, v15
	v_max3_f32 v96, v96, v14, v82
	v_pk_add_f32 v[88:89], v[90:91], v[136:137]
	v_pk_add_f32 v[90:91], v[94:95], v[138:139]
	v_add_f32_e32 v94, v250, v95
	v_max3_f32 v96, v96, v83, v100
	v_max3_f32 v97, v97, v102, v103
	v_pk_add_f32 v[106:107], v[92:93], v[122:123]
	v_add_f32_e32 v95, v215, v94
	v_max3_f32 v96, v96, v101, v84
	v_max3_f32 v97, v97, v86, v87
	v_pk_add_f32 v[92:93], v[94:95], v[140:141]
	v_add_f32_e32 v94, v215, v95
	v_max3_f32 v96, v96, v85, v104
	v_max3_f32 v97, v97, v106, v107
	v_add_f32_e32 v95, v215, v94
	v_max3_f32 v96, v96, v105, v88
	v_max3_f32 v97, v97, v90, v91
	v_pk_add_f32 v[94:95], v[94:95], v[142:143]
	v_max3_f32 v96, v96, v89, v108
	v_max3_f32 v97, v97, v110, v111
	v_max3_f32 v96, v96, v109, v92
	v_max3_f32 v97, v97, v94, v95
	v_add_f32_e32 v254, v1, v176
	v_max3_f32 v1, v96, v93, v97
	v_mov_b32_e32 v96, v1
	s_nop 1
	v_permlane32_swap_b32_e32 v1, v96
	v_max_f32_e32 v96, v96, v96
	v_max_f32_e32 v1, v1, v1
	v_max_f32_e32 v1, v1, v96
	v_cmp_lt_f32_e32 vcc, s20, v1
	s_cmp_lg_u64 vcc, 0
	s_cselect_b64 s[58:59], -1, 0
	s_cbranch_vccnz .LBB0_291

; template<int THRL,class Extra> __device__ __forceinline__ void attn_phase(char*lds,const AttnTensors&T,const unsigned*stats,unsigned*queue,volatile __attribute__((address_space(3))) unsigned*qw,const Extra&X){
;     ...
;   while(idx<N_UNITS+Extra::N){
;     X(idx-N_UNITS);
;     if(threadIdx.x==0)qw[0]=__hip_atomic_fetch_add(queue,1u,__ATOMIC_RELAXED,__HIP_MEMORY_SCOPE_AGENT);
;     asm volatile("s_waitcnt vmcnt(0) lgkmcnt(0)\n\ts_barrier":::"memory");
;     idx=__builtin_amdgcn_readfirstlane((int)qw[0]);
;     asm volatile("s_waitcnt lgkmcnt(0)\n\ts_barrier":::"memory");
;   }
.LBB0_363:
	s_or_b64 exec, exec, s[6:7]
	s_waitcnt vmcnt(0)
	v_readfirstlane_b32 s0, v2
	v_mov_b32_e32 v2, s23
	s_nop 0
	v_add_u32_e32 v1, s0, v1
	s_getreg_b32 s100, hwreg(HW_REG_XCC_ID, 0, 4)
	v_mov_b32_e32 v3, s100
	v_and_b32_e32 v3, 7, v3
	v_lshrrev_b32_e32 v4, 6, v1
	v_and_b32_e32 v4, 3, v4
	v_lshlrev_b32_e32 v4, 2, v4
	v_and_b32_e32 v5, 1, v3
	v_mul_u32_u24_e32 v5, 0x1122, v5
	v_xor_b32_e32 v5, 0x1267, v5
	v_lshrrev_b32_e32 v5, v4, v5
	v_and_b32_e32 v5, 15, v5
	v_sub_u32_e32 v5, 7, v5
	v_lshrrev_b32_e32 v4, 1, v3
	v_lshl_or_b32 v5, v4, 3, v5
	v_and_b32_e32 v4, 63, v1
	v_lshl_or_b32 v5, v4, 5, v5
	v_lshrrev_b32_e32 v4, 8, v1
	v_cmp_eq_u32_e64 s[100:101], 0, v4
	v_subrev_u32_e32 v4, 0x100, v1
	v_lshl_add_u32 v3, v3, 5, v4
	v_lshrrev_b32_e32 v4, 5, v4
	v_lshl_add_u32 v3, v4, 8, v3
	v_add_u32_e32 v3, 0x800, v3
	v_cndmask_b32_e64 v1, v3, v5, s[100:101]
	ds_write_b32 v2, v1
